# rope8 rewrite extended to the last group (256 sites, any SGPR temp pair)
# baseline (speedup 1.0000x reference)
; DI void rope8(float (&v)[8], const float* __restrict__ rope, int s, int fq) {
;     const f32x4 c0 = *(const f32x4*)(rope + s * 16), c1 = *(const f32x4*)(rope + s * 16 + 4), s0 = *(const f32x4*)(rope + s * 16 + 8), s1 = *(const f32x4*)(rope + s * 16 + 12);
;     const float cs[8] = {c0[0], c0[1], c0[2], c0[3], c1[0], c1[1], c1[2], c1[3]}, sn[8] = {s0[0], s0[1], s0[2], s0[3], s1[0], s1[1], s1[2], s1[3]};
; #pragma unroll
;     for (int e = 0; e < 8; ++e) {
;         const float other = __shfl_xor(v[e], 16);
;         const float a = v[e] * cs[e], bq = other * sn[e];
;         v[e] = (fq == 0) ? (a - bq) : ((fq == 1) ? (a + bq) : v[e]);
;     }
;     DI void operator()(const pg8::f32x4 (&acc)[2][2][4][2], const pg8::Unit& u, int wr, int wc, int fr, int fq) const {
;     ...
;                         if ((wc & 1) == 0) rope8(v, rope, s, fq);
.LBB0_2082:
	s_andn2_b64 vcc, exec, s[10:11]
	s_cbranch_vccnz .LBB0_2132
	v_and_b32_e32 v11, 64, v188
	v_xor_b32_e32 v10, 16, v188
	v_add_u32_e32 v11, 64, v11
	v_cmp_lt_i32_e32 vcc, v10, v11
	v_lshlrev_b32_e32 v74, 6, v83
	s_nop 0
	v_cndmask_b32_e32 v10, v188, v10, vcc
	v_lshlrev_b32_e32 v86, 2, v10
	global_load_dwordx4 v[78:81], v74, s[68:69]
	global_load_dwordx4 v[10:13], v74, s[68:69] offset:32
	global_load_dwordx4 v[14:17], v74, s[68:69] offset:48
	s_nop 0
	global_load_dwordx4 v[74:77], v74, s[68:69] offset:16
	v_mov_b32_e32 v224, v2
	v_mov_b32_e32 v225, v2
	v_cmp_eq_u32_e64 s[10:11], 1, v177
	s_nop 0
	v_permlane16_swap_b32_e32 v224, v225
	v_cndmask_b32_e64 v87, v225, v224, s[10:11]
	v_cmp_lt_i32_e32 vcc, 0, v177
	s_waitcnt vmcnt(3)
	v_mul_f32_e32 v78, v2, v78
	s_waitcnt vmcnt(2) lgkmcnt(0)
	v_mul_f32_e32 v87, v10, v87
	v_sub_f32_e32 v10, v78, v87
	v_add_f32_e32 v78, v78, v87
	v_cndmask_b32_e64 v78, v2, v78, s[10:11]
	v_cndmask_b32_e32 v10, v10, v78, vcc
	v_mov_b32_e32 v224, v3
	v_mov_b32_e32 v225, v3
	v_cmp_eq_u32_e64 s[10:11], 1, v177
	s_nop 0
	v_permlane16_swap_b32_e32 v224, v225
	v_cndmask_b32_e64 v87, v225, v224, s[10:11]
	v_mul_f32_e32 v78, v3, v79
	v_cmp_lt_i32_e32 vcc, 0, v177
	s_waitcnt lgkmcnt(0)
	v_mul_f32_e32 v79, v11, v87
	v_sub_f32_e32 v11, v78, v79
	v_add_f32_e32 v78, v78, v79
	v_cndmask_b32_e64 v78, v3, v78, s[10:11]
	v_cndmask_b32_e32 v11, v11, v78, vcc
	v_mov_b32_e32 v224, v4
	v_mov_b32_e32 v225, v4
	v_cmp_eq_u32_e64 s[10:11], 1, v177
	s_nop 0
	v_permlane16_swap_b32_e32 v224, v225
	v_cndmask_b32_e64 v79, v225, v224, s[10:11]
	v_mul_f32_e32 v78, v4, v80
	v_cmp_lt_i32_e32 vcc, 0, v177
	s_waitcnt lgkmcnt(0)
	v_mul_f32_e32 v79, v12, v79
	v_sub_f32_e32 v12, v78, v79
	v_add_f32_e32 v78, v78, v79
	v_cndmask_b32_e64 v78, v4, v78, s[10:11]
	v_cndmask_b32_e32 v12, v12, v78, vcc
	v_mov_b32_e32 v224, v5
	v_mov_b32_e32 v225, v5
	v_cmp_eq_u32_e64 s[10:11], 1, v177
	s_nop 0
	v_permlane16_swap_b32_e32 v224, v225
	v_cndmask_b32_e64 v79, v225, v224, s[10:11]
	v_mul_f32_e32 v78, v5, v81
	v_cmp_lt_i32_e32 vcc, 0, v177
	s_waitcnt lgkmcnt(0)
	v_mul_f32_e32 v79, v13, v79
	v_sub_f32_e32 v13, v78, v79
	v_add_f32_e32 v78, v78, v79
	v_cndmask_b32_e64 v78, v5, v78, s[10:11]
	v_cndmask_b32_e32 v13, v13, v78, vcc
	v_mov_b32_e32 v224, v6
	v_mov_b32_e32 v225, v6
	v_cmp_eq_u32_e64 s[10:11], 1, v177
	s_nop 0
	v_permlane16_swap_b32_e32 v224, v225
	v_cndmask_b32_e64 v78, v225, v224, s[10:11]
	s_waitcnt vmcnt(0)
	v_mul_f32_e32 v74, v6, v74
	v_cmp_lt_i32_e32 vcc, 0, v177
	s_waitcnt lgkmcnt(0)
	v_mul_f32_e32 v78, v14, v78
	v_sub_f32_e32 v14, v74, v78
	v_add_f32_e32 v74, v74, v78
	v_cndmask_b32_e64 v74, v6, v74, s[10:11]
	v_cndmask_b32_e32 v14, v14, v74, vcc
	v_mov_b32_e32 v224, v7
	v_mov_b32_e32 v225, v7
	v_cmp_eq_u32_e64 s[10:11], 1, v177
	s_nop 0
	v_permlane16_swap_b32_e32 v224, v225
	v_cndmask_b32_e64 v78, v225, v224, s[10:11]
	v_mul_f32_e32 v74, v7, v75
	v_cmp_lt_i32_e32 vcc, 0, v177
	s_waitcnt lgkmcnt(0)
	v_mul_f32_e32 v75, v15, v78
	v_sub_f32_e32 v15, v74, v75
	v_add_f32_e32 v74, v74, v75
	v_cndmask_b32_e64 v74, v7, v74, s[10:11]
	v_cndmask_b32_e32 v15, v15, v74, vcc
	v_mov_b32_e32 v224, v8
	v_mov_b32_e32 v225, v8
	v_cmp_eq_u32_e64 s[10:11], 1, v177
	s_nop 0
	v_permlane16_swap_b32_e32 v224, v225
	v_cndmask_b32_e64 v75, v225, v224, s[10:11]
	v_mul_f32_e32 v74, v8, v76
	v_cmp_lt_i32_e32 vcc, 0, v177
	s_waitcnt lgkmcnt(0)
	v_mul_f32_e32 v75, v16, v75
	v_sub_f32_e32 v16, v74, v75
	v_add_f32_e32 v74, v74, v75
	v_cndmask_b32_e64 v74, v8, v74, s[10:11]
	v_cndmask_b32_e32 v16, v16, v74, vcc
	v_mov_b32_e32 v224, v9
	v_mov_b32_e32 v225, v9
	v_cmp_eq_u32_e64 s[10:11], 1, v177
	s_nop 0
	v_permlane16_swap_b32_e32 v224, v225
	v_cndmask_b32_e64 v75, v225, v224, s[10:11]
	v_mul_f32_e32 v74, v9, v77
	v_cmp_lt_i32_e32 vcc, 0, v177
	s_waitcnt lgkmcnt(0)
	v_mul_f32_e32 v75, v17, v75
	v_sub_f32_e32 v17, v74, v75
	v_add_f32_e32 v74, v74, v75
	v_cndmask_b32_e64 v74, v9, v74, s[10:11]
	v_cndmask_b32_e32 v17, v17, v74, vcc
